# scan helper: rms-norm partial sums use DPP quad_perm moves instead of two ds_bpermute round trips per step (same summation order); plus attention QK read-ahead, packed forward substitution, DPP wave s
# baseline (speedup 1.0000x reference)
; DI void sh_load(const ScanH& k, int nc, u32x4 (&st)[14]) {
;     const size_t o8 = (size_t)nc * 8192; const int ht = k.ht;
; #pragma unroll
;     for (int i = 0; i < 4; ++i) { const int id = ht + 256 * i, r = id >> 4, cc = id & 15; st[i] = *(const u32x4*)(k.WC + o8 + r * 128 + cc * 8); st[4 + i] = *(const u32x4*)(k.QD + o8 + r * 128 + cc * 8); }
; #pragma unroll
;     for (int i = 0; i < 4; ++i) { const int id = ht + 256 * i, r = id >> 3, cc = id & 7; st[8 + i] = *(const u32x4*)(k.KD + o8 + r * 64 + cc * 8); }
; #pragma unroll
;     for (int i = 0; i < 2; ++i) { const int id = ht + 256 * i, r = id >> 3, cc = id & 7; st[12 + i] = *(const u32x4*)(k.AT + (size_t)nc * 4096 + r * 64 + cc * 8); }
; }
; DI void sh_store(const ScanH& k, int bf, const u32x4 (&st)[14]) {
;     LAS unsigned char* B_ = k.lds + bf * SC_BUF; const int ht = k.ht;
; #pragma unroll
;     for (int i = 0; i < 4; ++i) { const int id = ht + 256 * i, r = id >> 4, cc = id & 15;
;         *(LAS u32x2*)(B_ + SC_W + r * 264 + cc * 16) = (u32x2){st[i].x, st[i].y}; *(LAS u32x2*)(B_ + SC_W + r * 264 + cc * 16 + 8) = (u32x2){st[i].z, st[i].w};
;         *(LAS u32x2*)(B_ + SC_Q + r * 264 + cc * 16) = (u32x2){st[4 + i].x, st[4 + i].y}; *(LAS u32x2*)(B_ + SC_Q + r * 264 + cc * 16 + 8) = (u32x2){st[4 + i].z, st[4 + i].w}; }
; #pragma unroll
;     for (int i = 0; i < 4; ++i) { const int id = ht + 256 * i, r = id >> 3, cc = id & 7;
;         *(LAS u32x2*)(B_ + SC_K + r * 136 + cc * 16) = (u32x2){st[8 + i].x, st[8 + i].y}; *(LAS u32x2*)(B_ + SC_K + r * 136 + cc * 16 + 8) = (u32x2){st[8 + i].z, st[8 + i].w}; }
; #pragma unroll
;     for (int i = 0; i < 2; ++i) { const int id = ht + 256 * i, r = id >> 3, cc = id & 7;
;         *(LAS u32x2*)(B_ + SC_A + r * 136 + cc * 16) = (u32x2){st[12 + i].x, st[12 + i].y}; *(LAS u32x2*)(B_ + SC_A + r * 136 + cc * 16 + 8) = (u32x2){st[12 + i].z, st[12 + i].w}; }
; DI void scan_helper_step(const ScanH& k, int n, u32x4 (&stL)[14], const u32x4 (&stS)[14]) {
;     LAS unsigned char* lds = k.lds; const int bf = n & 1, tokb = k.b * SEQ + n * 64;
;     u32x4 zz[4];
;     { const bf16_t* zp = k.Zg + (size_t)(tokb + k.pt) * 512 + k.h * 128 + 32 * k.pseg;
; #pragma unroll
;       for (int i = 0; i < 4; ++i) zz[i] = *(const u32x4*)(zp + 8 * i); }
;     sh_load(k, n + 2 < 128 ? n + 2 : 127, stL);
;     sh_store(k, bf ^ 1, stS);
;     SC_RAW_BARRIER();
.LBB0_198:
	v_ashrrev_i32_e32 v151, 31, v150
	v_add_u32_e32 v58, 64, v150
	v_ashrrev_i32_e32 v59, 31, v58
	v_lshlrev_b64 v[58:59], 10, v[58:59]
	v_lshl_add_u64 v[58:59], v[152:153], 0, v[58:59]
	global_load_dwordx4 v[236:239], v[58:59], off offset:48
	global_load_dwordx4 v[240:243], v[58:59], off offset:32
	global_load_dwordx4 v[244:247], v[58:59], off offset:16
	global_load_dwordx4 v[248:251], v[58:59], off
	s_add_i32 s24, s40, 2
	v_add_u32_e32 v186, 0xea00, v159
	s_min_u32 s14, s24, 0x7d
	s_waitcnt vmcnt(17)
	ds_write2_b64 v186, v[2:3], v[4:5] offset1:1
	v_add_u32_e32 v2, v180, v158
	s_lshl_b32 s41, s14, 13
	s_waitcnt vmcnt(16)
	ds_write2_b64 v2, v[10:11], v[12:13] offset1:1
	v_add_u32_e32 v2, 0xea00, v162
	s_addk_i32 s41, 0x4000
	s_waitcnt vmcnt(15)
	ds_write2_b64 v2, v[6:7], v[8:9] offset1:1
	v_add_u32_e32 v2, v180, v161
	s_lshl_b32 s44, s41, 1
	s_waitcnt vmcnt(14)
	ds_write2_b64 v2, v[18:19], v[20:21] offset1:1
	v_add_u32_e32 v2, 0xea00, v165
	s_add_u32 s14, s4, s44
	s_waitcnt vmcnt(13)
	ds_write2_b64 v2, v[14:15], v[16:17] offset1:1
	v_add_u32_e32 v2, v180, v164
	s_addc_u32 s15, s5, 0
	s_waitcnt vmcnt(12)
	ds_write2_b64 v2, v[26:27], v[28:29] offset1:1
	v_add_u32_e32 v2, 0xea00, v168
	s_add_u32 s42, s6, s44
	s_waitcnt vmcnt(11)
	ds_write2_b64 v2, v[22:23], v[24:25] offset1:1
	v_add_u32_e32 v2, v180, v167
	s_addc_u32 s43, s7, 0
	s_waitcnt vmcnt(10)
	ds_write2_b64 v2, v[30:31], v[32:33] offset1:1
	v_add_u32_e32 v2, v181, v170
	v_lshl_add_u64 v[58:59], s[14:15], 0, v[134:135]
	v_lshl_add_u64 v[66:67], s[14:15], 0, v[136:137]
	v_lshl_add_u64 v[74:75], s[14:15], 0, v[138:139]
	v_lshl_add_u64 v[82:83], s[14:15], 0, v[140:141]
	s_add_u32 s14, s8, s44
	s_waitcnt vmcnt(9)
	ds_write2_b64 v2, v[34:35], v[36:37] offset1:1
	v_add_u32_e32 v2, v181, v172
	s_addc_u32 s15, s9, 0
	s_waitcnt vmcnt(8)
	ds_write2_b64 v2, v[38:39], v[40:41] offset1:1
	v_add_u32_e32 v2, v181, v174
	v_lshl_add_u64 v[90:91], s[14:15], 0, v[142:143]
	v_lshl_add_u64 v[94:95], s[14:15], 0, v[144:145]
	v_lshl_add_u64 v[98:99], s[14:15], 0, v[146:147]
	v_lshl_add_u64 v[102:103], s[14:15], 0, v[148:149]
	s_add_u32 s14, s10, s41
	s_waitcnt vmcnt(7)
	ds_write2_b64 v2, v[42:43], v[44:45] offset1:1
	v_add_u32_e32 v2, v181, v176
	s_addc_u32 s15, s11, 0
	s_waitcnt vmcnt(6)
	ds_write2_b64 v2, v[46:47], v[48:49] offset1:1
	v_add_u32_e32 v2, v182, v170
	v_lshl_add_u64 v[62:63], s[42:43], 0, v[134:135]
	v_lshl_add_u64 v[70:71], s[42:43], 0, v[136:137]
	v_lshl_add_u64 v[78:79], s[42:43], 0, v[138:139]
	v_lshl_add_u64 v[86:87], s[42:43], 0, v[140:141]
	v_mov_b32_e32 v157, v1
	v_lshl_add_u64 v[106:107], s[14:15], 0, v[142:143]
	v_lshl_add_u64 v[110:111], s[14:15], 0, v[144:145]
	s_waitcnt vmcnt(5)
	ds_write2_b64 v2, v[50:51], v[52:53] offset1:1
	v_add_u32_e32 v2, v182, v172
	v_lshl_add_u64 v[58:59], v[58:59], 0, v[0:1]
	v_lshl_add_u64 v[62:63], v[62:63], 0, v[0:1]
	v_lshl_add_u64 v[66:67], v[66:67], 0, v[0:1]
	v_lshl_add_u64 v[70:71], v[70:71], 0, v[0:1]
	v_lshl_add_u64 v[74:75], v[74:75], 0, v[0:1]
	v_lshl_add_u64 v[78:79], v[78:79], 0, v[0:1]
	v_lshl_add_u64 v[82:83], v[82:83], 0, v[0:1]
	v_lshl_add_u64 v[86:87], v[86:87], 0, v[0:1]
	v_lshl_add_u64 v[90:91], v[90:91], 0, v[156:157]
	v_lshl_add_u64 v[94:95], v[94:95], 0, v[156:157]
	v_lshl_add_u64 v[98:99], v[98:99], 0, v[156:157]
	v_lshl_add_u64 v[102:103], v[102:103], 0, v[156:157]
	v_lshl_add_u64 v[106:107], v[106:107], 0, v[156:157]
	v_lshl_add_u64 v[110:111], v[110:111], 0, v[156:157]
	s_waitcnt vmcnt(4)
	ds_write2_b64 v2, v[54:55], v[56:57] offset1:1
	global_load_dwordx4 v[58:61], v[58:59], off
	s_add_i32 s14, s40, 3
	global_load_dwordx4 v[62:65], v[62:63], off
	s_min_u32 s14, s14, 0x7d
	global_load_dwordx4 v[66:69], v[66:67], off
	s_lshl_b32 s14, s14, 13
	global_load_dwordx4 v[70:73], v[70:71], off
	v_lshlrev_b32_e32 v228, 16, v118
	global_load_dwordx4 v[74:77], v[74:75], off
	v_and_b32_e32 v229, 0xffff0000, v118
	global_load_dwordx4 v[78:81], v[78:79], off
	v_lshlrev_b32_e32 v56, 16, v128
	global_load_dwordx4 v[82:85], v[82:83], off
	v_and_b32_e32 v57, 0xffff0000, v128
	global_load_dwordx4 v[86:89], v[86:87], off
	v_lshlrev_b32_e32 v192, 16, v127
	global_load_dwordx4 v[90:93], v[90:91], off
	v_and_b32_e32 v193, 0xffff0000, v127
	global_load_dwordx4 v[94:97], v[94:95], off
	v_lshlrev_b32_e32 v202, 16, v126
	global_load_dwordx4 v[98:101], v[98:99], off
	v_and_b32_e32 v203, 0xffff0000, v126
	global_load_dwordx4 v[102:105], v[102:103], off
	v_lshlrev_b32_e32 v126, 16, v129
	global_load_dwordx4 v[106:109], v[106:107], off
	v_and_b32_e32 v127, 0xffff0000, v129
	global_load_dwordx4 v[110:113], v[110:111], off
	s_waitcnt lgkmcnt(0)
	s_barrier
; #define LAS __attribute__((address_space(3)))
; DI unsigned pk2(float lo, float hi) { f32x2 v = {lo, hi}; bf16x2_t b = __builtin_convertvector(v, bf16x2_t); return __builtin_bit_cast(unsigned, b); }
; DI float lo_bf(unsigned u) { return __uint_as_float(u << 16); }
; DI float hi_bf(unsigned u) { return __uint_as_float(u & 0xffff0000u); }
; DI void scan_helper_step(const ScanH& k, int n, u32x4 (&stL)[14], const u32x4 (&stS)[14]) {
;     ...
;     const LAS unsigned char* ob = lds + SC_O + bf * SC_OSZ + k.pt * 272 + k.pseg * 64;
;     const LAS float* gmL = (const LAS float*)(lds + SC_O + 2 * SC_OSZ + 512) + 32 * k.pseg;
;     u32x4 ov4[4];
; #pragma unroll
;     for (int i = 0; i < 4; ++i) ov4[i] = *(const LAS u32x4*)(ob + 16 * i);
;     float ss = 0.f;
; #pragma unroll
;     for (int i = 0; i < 4; ++i)
; #pragma unroll
;         for (int j = 0; j < 4; ++j) { const float a = lo_bf(ov4[i][j]), b2 = hi_bf(ov4[i][j]); ss += a * a + b2 * b2; }
;     ss += __shfl_xor(ss, 1); ss += __shfl_xor(ss, 2);
;     const float rs = __builtin_amdgcn_rsqf(ss * (1.f / 128.f) + RMS_EPS);
;     bf16_t* mp = k.MIX + (size_t)(tokb + k.pt) * DM + k.h * 128 + 32 * k.pseg;
; #pragma unroll
;     for (int i = 0; i < 4; ++i) { u32x4 res;
; #pragma unroll
;         for (int j = 0; j < 4; ++j) { const int e = 8 * i + 2 * j;
;             const float a0 = lo_bf(ov4[i][j]) * rs * gmL[e] * lo_bf(zz[i][j]), a1 = hi_bf(ov4[i][j]) * rs * gmL[e + 1] * hi_bf(zz[i][j]); res[j] = pk2(a0, a1); }
;         *(u32x4*)(mp + 8 * i) = res; }
	ds_read_b128 v[14:17], v183
	ds_read_b128 v[18:21], v183 offset:16
	ds_read_b128 v[22:25], v183 offset:32
	ds_read_b128 v[2:5], v183 offset:48
	v_lshlrev_b32_e32 v210, 16, v124
	s_waitcnt lgkmcnt(3)
	v_lshlrev_b32_e32 v188, 16, v15
	v_and_b32_e32 v189, 0xffff0000, v15
	s_waitcnt lgkmcnt(1)
	v_and_b32_e32 v13, 0xffff0000, v25
	v_and_b32_e32 v12, 0xffff0000, v24
	v_lshlrev_b32_e32 v11, 16, v25
	v_lshlrev_b32_e32 v10, 16, v24
	v_pk_mul_f32 v[6:7], v[12:13], v[12:13]
	s_waitcnt lgkmcnt(0)
	v_and_b32_e32 v9, 0xffff0000, v3
	v_and_b32_e32 v8, 0xffff0000, v2
	v_pk_fma_f32 v[40:41], v[10:11], v[10:11], v[6:7]
	v_lshlrev_b32_e32 v7, 16, v3
	v_lshlrev_b32_e32 v6, 16, v2
	v_pk_mul_f32 v[2:3], v[8:9], v[8:9]
	v_lshlrev_b32_e32 v198, 16, v14
	v_pk_fma_f32 v[42:43], v[6:7], v[6:7], v[2:3]
	v_lshlrev_b32_e32 v3, 16, v5
	v_lshlrev_b32_e32 v2, 16, v4
	v_and_b32_e32 v5, 0xffff0000, v5
	v_and_b32_e32 v4, 0xffff0000, v4
	v_pk_mul_f32 v[24:25], v[4:5], v[4:5]
	v_and_b32_e32 v199, 0xffff0000, v14
	v_pk_fma_f32 v[44:45], v[2:3], v[2:3], v[24:25]
	v_and_b32_e32 v25, 64, v230
	v_xor_b32_e32 v24, 1, v230
	v_add_u32_e32 v25, 64, v25
	v_cmp_lt_i32_e32 vcc, v24, v25
	v_lshlrev_b32_e32 v52, 16, v16
	v_and_b32_e32 v53, 0xffff0000, v16
	v_cndmask_b32_e32 v24, v230, v24, vcc
	v_lshlrev_b32_e32 v186, 2, v24
	v_xor_b32_e32 v24, 2, v230
	v_cmp_lt_i32_e32 vcc, v24, v25
	v_pk_mul_f32 v[190:191], v[188:189], v[188:189]
	v_pk_mul_f32 v[200:201], v[198:199], v[198:199]
	v_cndmask_b32_e32 v24, v230, v24, vcc
	v_lshlrev_b32_e32 v187, 2, v24
	v_lshlrev_b64 v[24:25], 11, v[150:151]
	v_lshlrev_b32_e32 v48, 16, v17
	v_and_b32_e32 v49, 0xffff0000, v17
	v_pk_mul_f32 v[54:55], v[52:53], v[52:53]
	v_add_f32_e32 v118, v190, v191
	v_add_f32_e32 v151, v200, v201
	v_pk_mul_f32 v[50:51], v[48:49], v[48:49]
	v_lshlrev_b32_e32 v218, 16, v18
	v_and_b32_e32 v219, 0xffff0000, v18
	v_add_f32_e32 v118, v151, v118
	v_add_f32_e32 v54, v54, v55
	v_lshlrev_b32_e32 v212, 16, v19
	v_and_b32_e32 v213, 0xffff0000, v19
	v_pk_mul_f32 v[18:19], v[218:219], v[218:219]
	v_add_f32_e32 v54, v54, v118
	v_add_f32_e32 v50, v50, v51
	v_lshlrev_b32_e32 v208, 16, v20
	v_and_b32_e32 v209, 0xffff0000, v20
	v_pk_mul_f32 v[214:215], v[212:213], v[212:213]
	v_add_f32_e32 v50, v50, v54
	v_add_f32_e32 v18, v18, v19
	v_lshlrev_b32_e32 v128, 16, v21
	v_and_b32_e32 v129, 0xffff0000, v21
	v_pk_mul_f32 v[20:21], v[208:209], v[208:209]
	v_add_f32_e32 v18, v18, v50
	v_add_f32_e32 v19, v214, v215
	v_pk_mul_f32 v[204:205], v[128:129], v[128:129]
	v_lshlrev_b32_e32 v224, 16, v22
	v_and_b32_e32 v225, 0xffff0000, v22
	v_add_f32_e32 v18, v19, v18
	v_add_f32_e32 v19, v20, v21
	v_and_b32_e32 v211, 0xffff0000, v124
	v_lshlrev_b32_e32 v216, 16, v123
	v_and_b32_e32 v217, 0xffff0000, v123
	v_lshlrev_b32_e32 v220, 16, v122
	v_and_b32_e32 v221, 0xffff0000, v122
	v_lshlrev_b32_e32 v122, 16, v125
	v_and_b32_e32 v123, 0xffff0000, v125
	v_lshlrev_b32_e32 v124, 16, v23
	v_and_b32_e32 v125, 0xffff0000, v23
	v_pk_mul_f32 v[22:23], v[224:225], v[224:225]
	v_add_f32_e32 v18, v19, v18
	v_add_f32_e32 v19, v204, v205
	v_pk_mul_f32 v[222:223], v[124:125], v[124:125]
	v_add_f32_e32 v18, v19, v18
	v_add_f32_e32 v19, v22, v23
	v_add_f32_e32 v18, v19, v18
	v_add_f32_e32 v19, v222, v223
	v_add_f32_e32 v18, v19, v18
	v_add_f32_e32 v18, v40, v18
	v_add_f32_e32 v18, v41, v18
	v_add_f32_e32 v18, v42, v18
	v_add_f32_e32 v18, v43, v18
	v_add_f32_e32 v18, v44, v18
	v_add_f32_e32 v18, v45, v18
	s_nop 1
	v_mov_b32_dpp v19, v18 quad_perm:[1,0,3,2] row_mask:0xf bank_mask:0xf
	v_lshl_add_u64 v[46:47], v[154:155], 0, v[24:25]
	ds_read_b128 v[24:27], v184
	ds_read_b128 v[28:31], v184 offset:16
	ds_read_b128 v[32:35], v184 offset:32
	ds_read_b128 v[36:39], v184 offset:48
	ds_read_b128 v[14:17], v184 offset:64
	s_add_i32 s42, s14, 0x4000
	s_waitcnt lgkmcnt(5)
	v_add_f32_e32 v18, v18, v19
	s_nop 1
	v_mov_b32_dpp v19, v18 quad_perm:[2,3,0,1] row_mask:0xf bank_mask:0xf
	s_lshl_b32 s43, s42, 1
	s_add_u32 s14, s4, s43
	s_addc_u32 s15, s5, 0
	s_add_u32 s40, s6, s43
	s_waitcnt lgkmcnt(0)
	v_add_f32_e32 v18, v18, v19
	v_fmamk_f32 v18, v18, 0x3c000000, v231
	v_rsq_f32_e32 v22, v18
	s_addc_u32 s41, s7, 0
	v_pk_mul_f32 v[18:19], v[22:23], v[198:199] op_sel_hi:[0,1]
	v_pk_mul_f32 v[20:21], v[22:23], v[188:189] op_sel_hi:[0,1]
	v_pk_mul_f32 v[18:19], v[24:25], v[18:19]
	v_pk_mul_f32 v[20:21], v[26:27], v[20:21]
	v_pk_mul_f32 v[18:19], v[18:19], v[202:203]
	v_pk_mul_f32 v[20:21], v[20:21], v[192:193]
	v_cvt_pk_bf16_f32 v18, v18, v19
	v_cvt_pk_bf16_f32 v19, v20, v21
	v_pk_mul_f32 v[20:21], v[22:23], v[52:53] op_sel_hi:[0,1]
	v_pk_mul_f32 v[24:25], v[22:23], v[48:49] op_sel_hi:[0,1]
	v_pk_mul_f32 v[20:21], v[28:29], v[20:21]
	v_pk_mul_f32 v[24:25], v[30:31], v[24:25]
	v_pk_mul_f32 v[20:21], v[20:21], v[56:57]
	v_pk_mul_f32 v[24:25], v[24:25], v[126:127]
	v_cvt_pk_bf16_f32 v20, v20, v21
	v_cvt_pk_bf16_f32 v21, v24, v25
	global_store_dwordx4 v[46:47], v[18:21], off
	v_pk_mul_f32 v[24:25], v[22:23], v[128:129] op_sel_hi:[0,1]
	v_pk_mul_f32 v[24:25], v[38:39], v[24:25]
	v_pk_mul_f32 v[18:19], v[22:23], v[218:219] op_sel_hi:[0,1]
	v_pk_mul_f32 v[20:21], v[22:23], v[212:213] op_sel_hi:[0,1]
	v_pk_mul_f32 v[18:19], v[32:33], v[18:19]
	v_pk_mul_f32 v[20:21], v[34:35], v[20:21]
	v_pk_mul_f32 v[18:19], v[18:19], v[220:221]
	v_pk_mul_f32 v[20:21], v[20:21], v[216:217]
	v_cvt_pk_bf16_f32 v18, v18, v19
	v_cvt_pk_bf16_f32 v19, v20, v21
	v_pk_mul_f32 v[20:21], v[22:23], v[208:209] op_sel_hi:[0,1]
	v_pk_mul_f32 v[20:21], v[36:37], v[20:21]
	v_pk_mul_f32 v[24:25], v[24:25], v[122:123]
	v_pk_mul_f32 v[20:21], v[20:21], v[210:211]
	v_add_u32_e32 v188, 64, v150
	v_cvt_pk_bf16_f32 v20, v20, v21
	v_cvt_pk_bf16_f32 v21, v24, v25
	global_store_dwordx4 v[46:47], v[18:21], off offset:16
	v_ashrrev_i32_e32 v189, 31, v188
	v_lshl_add_u64 v[30:31], s[40:41], 0, v[140:141]
	v_pk_mul_f32 v[18:19], v[22:23], v[224:225] op_sel_hi:[0,1]
	v_pk_mul_f32 v[14:15], v[18:19], v[14:15]
	v_pk_mul_f32 v[18:19], v[22:23], v[124:125] op_sel_hi:[0,1]
	v_pk_mul_f32 v[16:17], v[18:19], v[16:17]
	v_lshlrev_b32_e32 v18, 16, v119
	v_and_b32_e32 v19, 0xffff0000, v119
	v_pk_mul_f32 v[14:15], v[14:15], v[228:229]
	v_pk_mul_f32 v[16:17], v[16:17], v[18:19]
	v_cvt_pk_bf16_f32 v14, v14, v15
	v_cvt_pk_bf16_f32 v15, v16, v17
	v_mov_b32_e32 v16, v10
	v_mov_b32_e32 v17, v12
	v_pk_mul_f32 v[20:21], v[22:23], v[16:17] op_sel_hi:[0,1]
	ds_read_b128 v[16:19], v184 offset:80
	v_mov_b32_e32 v12, v11
	v_pk_mul_f32 v[10:11], v[22:23], v[12:13] op_sel_hi:[0,1]
	v_lshlrev_b32_e32 v12, 16, v121
	v_and_b32_e32 v13, 0xffff0000, v121
	s_waitcnt lgkmcnt(0)
; DI void sh_load(const ScanH& k, int nc, u32x4 (&st)[14]) {
;     const size_t o8 = (size_t)nc * 8192; const int ht = k.ht;
; #pragma unroll
;     for (int i = 0; i < 4; ++i) { const int id = ht + 256 * i, r = id >> 4, cc = id & 15; st[i] = *(const u32x4*)(k.WC + o8 + r * 128 + cc * 8); st[4 + i] = *(const u32x4*)(k.QD + o8 + r * 128 + cc * 8); }
; #pragma unroll
;     for (int i = 0; i < 4; ++i) { const int id = ht + 256 * i, r = id >> 3, cc = id & 7; st[8 + i] = *(const u32x4*)(k.KD + o8 + r * 64 + cc * 8); }
; #pragma unroll
;     for (int i = 0; i < 2; ++i) { const int id = ht + 256 * i, r = id >> 3, cc = id & 7; st[12 + i] = *(const u32x4*)(k.AT + (size_t)nc * 4096 + r * 64 + cc * 8); }
; }
; DI void sh_store(const ScanH& k, int bf, const u32x4 (&st)[14]) {
;     LAS unsigned char* B_ = k.lds + bf * SC_BUF; const int ht = k.ht;
; #pragma unroll
;     for (int i = 0; i < 4; ++i) { const int id = ht + 256 * i, r = id >> 4, cc = id & 15;
;         *(LAS u32x2*)(B_ + SC_W + r * 264 + cc * 16) = (u32x2){st[i].x, st[i].y}; *(LAS u32x2*)(B_ + SC_W + r * 264 + cc * 16 + 8) = (u32x2){st[i].z, st[i].w};
;         *(LAS u32x2*)(B_ + SC_Q + r * 264 + cc * 16) = (u32x2){st[4 + i].x, st[4 + i].y}; *(LAS u32x2*)(B_ + SC_Q + r * 264 + cc * 16 + 8) = (u32x2){st[4 + i].z, st[4 + i].w}; }
; #pragma unroll
;     for (int i = 0; i < 4; ++i) { const int id = ht + 256 * i, r = id >> 3, cc = id & 7;
;         *(LAS u32x2*)(B_ + SC_K + r * 136 + cc * 16) = (u32x2){st[8 + i].x, st[8 + i].y}; *(LAS u32x2*)(B_ + SC_K + r * 136 + cc * 16 + 8) = (u32x2){st[8 + i].z, st[8 + i].w}; }
; #pragma unroll
;     for (int i = 0; i < 2; ++i) { const int id = ht + 256 * i, r = id >> 3, cc = id & 7;
;         *(LAS u32x2*)(B_ + SC_A + r * 136 + cc * 16) = (u32x2){st[12 + i].x, st[12 + i].y}; *(LAS u32x2*)(B_ + SC_A + r * 136 + cc * 16 + 8) = (u32x2){st[12 + i].z, st[12 + i].w}; }
; }
; DI void scan_helper_step(const ScanH& k, int n, u32x4 (&stL)[14], const u32x4 (&stS)[14]) {
;     LAS unsigned char* lds = k.lds; const int bf = n & 1, tokb = k.b * SEQ + n * 64;
;     ...
;     for (int i = 0; i < 4; ++i) { u32x4 res;
; #pragma unroll
;         for (int j = 0; j < 4; ++j) { const int e = 8 * i + 2 * j;
;             const float a0 = lo_bf(ov4[i][j]) * rs * gmL[e] * lo_bf(zz[i][j]), a1 = hi_bf(ov4[i][j]) * rs * gmL[e + 1] * hi_bf(zz[i][j]); res[j] = pk2(a0, a1); }
;         *(u32x4*)(mp + 8 * i) = res; }
	v_pk_mul_f32 v[16:17], v[20:21], v[16:17]
	v_lshlrev_b32_e32 v20, 16, v120
	v_and_b32_e32 v21, 0xffff0000, v120
	v_pk_mul_f32 v[10:11], v[10:11], v[18:19]
	v_pk_mul_f32 v[16:17], v[16:17], v[20:21]
	v_pk_mul_f32 v[10:11], v[10:11], v[12:13]
	v_cvt_pk_bf16_f32 v16, v16, v17
	v_cvt_pk_bf16_f32 v17, v10, v11
	v_mov_b32_e32 v10, v6
	v_mov_b32_e32 v11, v8
	global_store_dwordx4 v[46:47], v[14:17], off offset:32
	v_mov_b32_e32 v8, v7
	v_pk_mul_f32 v[8:9], v[22:23], v[8:9] op_sel_hi:[0,1]
	v_pk_mul_f32 v[14:15], v[22:23], v[10:11] op_sel_hi:[0,1]
	ds_read_b128 v[10:13], v184 offset:96
	v_lshl_add_u64 v[30:31], v[30:31], 0, v[0:1]
	v_add_u32_e32 v150, 0x80, v150
	s_waitcnt lgkmcnt(0)
	v_pk_mul_f32 v[10:11], v[14:15], v[10:11]
	v_lshlrev_b32_e32 v14, 16, v114
	v_and_b32_e32 v15, 0xffff0000, v114
	v_pk_mul_f32 v[10:11], v[10:11], v[14:15]
	v_pk_mul_f32 v[8:9], v[8:9], v[12:13]
	v_cvt_pk_bf16_f32 v6, v10, v11
	v_lshlrev_b32_e32 v10, 16, v115
	v_and_b32_e32 v11, 0xffff0000, v115
	v_pk_mul_f32 v[8:9], v[8:9], v[10:11]
	v_lshl_add_u64 v[14:15], s[40:41], 0, v[136:137]
	v_cvt_pk_bf16_f32 v7, v8, v9
	v_mov_b32_e32 v8, v2
	v_mov_b32_e32 v9, v4
	v_pk_mul_f32 v[12:13], v[22:23], v[8:9] op_sel_hi:[0,1]
	ds_read_b128 v[8:11], v184 offset:112
	v_mov_b32_e32 v4, v3
	v_pk_mul_f32 v[2:3], v[22:23], v[4:5] op_sel_hi:[0,1]
	v_lshlrev_b32_e32 v4, 16, v117
	v_and_b32_e32 v5, 0xffff0000, v117
	s_waitcnt lgkmcnt(0)
	v_pk_mul_f32 v[8:9], v[12:13], v[8:9]
	v_lshlrev_b32_e32 v12, 16, v116
	v_and_b32_e32 v13, 0xffff0000, v116
	v_pk_mul_f32 v[2:3], v[2:3], v[10:11]
	v_pk_mul_f32 v[8:9], v[8:9], v[12:13]
	v_pk_mul_f32 v[2:3], v[2:3], v[4:5]
	v_cvt_pk_bf16_f32 v8, v8, v9
	v_cvt_pk_bf16_f32 v9, v2, v3
	v_add_u32_e32 v2, 64, v188
	v_ashrrev_i32_e32 v3, 31, v2
	v_lshlrev_b64 v[2:3], 10, v[2:3]
	global_store_dwordx4 v[46:47], v[6:9], off offset:48
	v_lshl_add_u64 v[2:3], v[152:153], 0, v[2:3]
	global_load_dwordx4 v[114:117], v[2:3], off offset:48
	global_load_dwordx4 v[118:121], v[2:3], off offset:32
	global_load_dwordx4 v[122:125], v[2:3], off offset:16
	global_load_dwordx4 v[126:129], v[2:3], off
	v_lshl_add_u64 v[2:3], s[14:15], 0, v[134:135]
	v_lshl_add_u64 v[6:7], s[40:41], 0, v[134:135]
	v_lshl_add_u64 v[2:3], v[2:3], 0, v[0:1]
	v_lshl_add_u64 v[6:7], v[6:7], 0, v[0:1]
	global_load_dwordx4 v[2:5], v[2:3], off
	v_lshl_add_u64 v[14:15], v[14:15], 0, v[0:1]
	global_load_dwordx4 v[10:13], v[6:7], off
	v_lshl_add_u64 v[6:7], s[14:15], 0, v[136:137]
	v_lshl_add_u64 v[6:7], v[6:7], 0, v[0:1]
	global_load_dwordx4 v[6:9], v[6:7], off
	v_lshl_add_u64 v[22:23], s[40:41], 0, v[138:139]
	global_load_dwordx4 v[18:21], v[14:15], off
	v_lshl_add_u64 v[14:15], s[14:15], 0, v[138:139]
	v_lshl_add_u64 v[14:15], v[14:15], 0, v[0:1]
	v_lshl_add_u64 v[22:23], v[22:23], 0, v[0:1]
	global_load_dwordx4 v[14:17], v[14:15], off
	s_mov_b32 s40, s24
	global_load_dwordx4 v[26:29], v[22:23], off
	v_lshl_add_u64 v[22:23], s[14:15], 0, v[140:141]
	s_add_u32 s14, s8, s43
	s_addc_u32 s15, s9, 0
	v_lshl_add_u64 v[34:35], s[14:15], 0, v[142:143]
	v_lshl_add_u64 v[38:39], s[14:15], 0, v[144:145]
	v_lshl_add_u64 v[42:43], s[14:15], 0, v[146:147]
	v_lshl_add_u64 v[46:47], s[14:15], 0, v[148:149]
	s_add_u32 s14, s10, s42
	s_addc_u32 s15, s11, 0
	v_lshl_add_u64 v[50:51], s[14:15], 0, v[142:143]
	v_lshl_add_u64 v[54:55], s[14:15], 0, v[144:145]
	v_lshl_add_u64 v[22:23], v[22:23], 0, v[0:1]
	v_lshl_add_u64 v[34:35], v[34:35], 0, v[156:157]
	v_lshl_add_u64 v[38:39], v[38:39], 0, v[156:157]
	v_lshl_add_u64 v[42:43], v[42:43], 0, v[156:157]
	v_lshl_add_u64 v[46:47], v[46:47], 0, v[156:157]
	v_lshl_add_u64 v[50:51], v[50:51], 0, v[156:157]
	v_lshl_add_u64 v[54:55], v[54:55], 0, v[156:157]
	global_load_dwordx4 v[22:25], v[22:23], off
	s_cmpk_gt_u32 s24, 0x7d
	global_load_dwordx4 v[30:33], v[30:31], off
	s_waitcnt vmcnt(16)
	v_lshlrev_b32_e32 v228, 16, v240
	global_load_dwordx4 v[34:37], v[34:35], off
	v_and_b32_e32 v229, 0xffff0000, v240
	global_load_dwordx4 v[38:41], v[38:39], off
	v_lshlrev_b32_e32 v192, 16, v249
	global_load_dwordx4 v[42:45], v[42:43], off
	v_and_b32_e32 v193, 0xffff0000, v249
	global_load_dwordx4 v[46:49], v[46:47], off
	v_lshlrev_b32_e32 v202, 16, v248
	global_load_dwordx4 v[50:53], v[50:51], off
	v_and_b32_e32 v203, 0xffff0000, v248
	global_load_dwordx4 v[54:57], v[54:55], off
	s_waitcnt vmcnt(22)
	ds_write2_b64 v159, v[58:59], v[60:61] offset1:1
	ds_write2_b64 v160, v[62:63], v[64:65] offset1:1
	ds_write2_b64 v162, v[66:67], v[68:69] offset1:1
	ds_write2_b64 v163, v[70:71], v[72:73] offset1:1
	ds_write2_b64 v165, v[74:75], v[76:77] offset1:1
	ds_write2_b64 v166, v[78:79], v[80:81] offset1:1
	ds_write2_b64 v168, v[82:83], v[84:85] offset1:1
	ds_write2_b64 v169, v[86:87], v[88:89] offset1:1
	ds_write2_b64 v171, v[90:91], v[92:93] offset1:1
	ds_write2_b64 v173, v[94:95], v[96:97] offset1:1
	ds_write2_b64 v175, v[98:99], v[100:101] offset1:1
	ds_write2_b64 v177, v[102:103], v[104:105] offset1:1
	ds_write2_b64 v178, v[106:107], v[108:109] offset1:1
	ds_write2_b64 v179, v[110:111], v[112:113] offset1:1
	s_waitcnt lgkmcnt(0)
	s_barrier
; #define LAS __attribute__((address_space(3)))
; DI float lo_bf(unsigned u) { return __uint_as_float(u << 16); }
; DI float hi_bf(unsigned u) { return __uint_as_float(u & 0xffff0000u); }
; DI void scan_helper_step(const ScanH& k, int n, u32x4 (&stL)[14], const u32x4 (&stS)[14]) {
;     ...
;     const LAS unsigned char* ob = lds + SC_O + bf * SC_OSZ + k.pt * 272 + k.pseg * 64;
;     const LAS float* gmL = (const LAS float*)(lds + SC_O + 2 * SC_OSZ + 512) + 32 * k.pseg;
;     u32x4 ov4[4];
; #pragma unroll
;     for (int i = 0; i < 4; ++i) ov4[i] = *(const LAS u32x4*)(ob + 16 * i);
;     float ss = 0.f;
; #pragma unroll
;     for (int i = 0; i < 4; ++i)
; #pragma unroll
;         for (int j = 0; j < 4; ++j) { const float a = lo_bf(ov4[i][j]), b2 = hi_bf(ov4[i][j]); ss += a * a + b2 * b2; }
;     ss += __shfl_xor(ss, 1); ss += __shfl_xor(ss, 2);
;     const float rs = __builtin_amdgcn_rsqf(ss * (1.f / 128.f) + RMS_EPS);
	ds_read_b128 v[58:61], v185
	ds_read_b128 v[62:65], v185 offset:16
	ds_read_b128 v[66:69], v185 offset:32
	ds_read_b128 v[70:73], v185 offset:48
	v_lshlrev_b32_e32 v112, 16, v250
	s_waitcnt lgkmcnt(3)
	v_lshlrev_b32_e32 v198, 16, v58
	v_and_b32_e32 v199, 0xffff0000, v58
	s_waitcnt lgkmcnt(1)
	v_and_b32_e32 v87, 0xffff0000, v69
	v_and_b32_e32 v86, 0xffff0000, v68
	v_lshlrev_b32_e32 v85, 16, v69
	v_lshlrev_b32_e32 v84, 16, v68
	v_pk_mul_f32 v[68:69], v[86:87], v[86:87]
	s_waitcnt lgkmcnt(0)
	v_and_b32_e32 v93, 0xffff0000, v71
	v_and_b32_e32 v92, 0xffff0000, v70
	v_pk_fma_f32 v[88:89], v[84:85], v[84:85], v[68:69]
	v_lshlrev_b32_e32 v91, 16, v71
	v_lshlrev_b32_e32 v90, 16, v70
	v_pk_mul_f32 v[68:69], v[92:93], v[92:93]
	v_and_b32_e32 v99, 0xffff0000, v73
	v_and_b32_e32 v98, 0xffff0000, v72
	v_pk_fma_f32 v[94:95], v[90:91], v[90:91], v[68:69]
	v_lshlrev_b32_e32 v97, 16, v73
	v_lshlrev_b32_e32 v96, 16, v72
	v_pk_mul_f32 v[68:69], v[98:99], v[98:99]
	v_lshlrev_b32_e32 v108, 16, v60
	v_pk_fma_f32 v[100:101], v[96:97], v[96:97], v[68:69]
	v_lshlrev_b64 v[68:69], 11, v[188:189]
	v_lshlrev_b32_e32 v188, 16, v59
	v_and_b32_e32 v189, 0xffff0000, v59
	v_and_b32_e32 v109, 0xffff0000, v60
	v_pk_mul_f32 v[190:191], v[188:189], v[188:189]
	v_pk_mul_f32 v[200:201], v[198:199], v[198:199]
	v_lshlrev_b32_e32 v104, 16, v61
	v_and_b32_e32 v105, 0xffff0000, v61
	v_pk_mul_f32 v[110:111], v[108:109], v[108:109]
	v_add_f32_e32 v240, v190, v191
	v_add_f32_e32 v151, v200, v201
	v_pk_mul_f32 v[106:107], v[104:105], v[104:105]
	v_lshlrev_b32_e32 v218, 16, v62
	v_and_b32_e32 v219, 0xffff0000, v62
	v_add_f32_e32 v240, v151, v240
	v_add_f32_e32 v110, v110, v111
	v_lshlrev_b32_e32 v212, 16, v63
	v_and_b32_e32 v213, 0xffff0000, v63
	v_pk_mul_f32 v[62:63], v[218:219], v[218:219]
	v_add_f32_e32 v110, v110, v240
	v_add_f32_e32 v106, v106, v107
	v_lshlrev_b32_e32 v208, 16, v64
	v_and_b32_e32 v209, 0xffff0000, v64
	v_pk_mul_f32 v[214:215], v[212:213], v[212:213]
	v_add_f32_e32 v106, v106, v110
	v_add_f32_e32 v62, v62, v63
	v_and_b32_e32 v113, 0xffff0000, v250
	v_lshlrev_b32_e32 v248, 16, v251
	v_and_b32_e32 v249, 0xffff0000, v251
	v_lshlrev_b32_e32 v250, 16, v65
	v_and_b32_e32 v251, 0xffff0000, v65
	v_pk_mul_f32 v[64:65], v[208:209], v[208:209]
	v_add_f32_e32 v62, v62, v106
	v_add_f32_e32 v63, v214, v215
	v_pk_mul_f32 v[204:205], v[250:251], v[250:251]
	v_lshlrev_b32_e32 v224, 16, v66
	v_and_b32_e32 v225, 0xffff0000, v66
	v_add_f32_e32 v62, v63, v62
	v_add_f32_e32 v63, v64, v65
	v_lshlrev_b32_e32 v210, 16, v246
	v_and_b32_e32 v211, 0xffff0000, v246
	v_lshlrev_b32_e32 v216, 16, v245
	v_and_b32_e32 v217, 0xffff0000, v245
	v_lshlrev_b32_e32 v220, 16, v244
	v_and_b32_e32 v221, 0xffff0000, v244
	v_lshlrev_b32_e32 v244, 16, v247
	v_and_b32_e32 v245, 0xffff0000, v247
	v_lshlrev_b32_e32 v246, 16, v67
	v_and_b32_e32 v247, 0xffff0000, v67
	v_pk_mul_f32 v[66:67], v[224:225], v[224:225]
	v_add_f32_e32 v62, v63, v62
	v_add_f32_e32 v63, v204, v205
	v_pk_mul_f32 v[222:223], v[246:247], v[246:247]
	v_add_f32_e32 v62, v63, v62
	v_add_f32_e32 v63, v66, v67
	v_add_f32_e32 v62, v63, v62
	v_add_f32_e32 v63, v222, v223
	v_add_f32_e32 v62, v63, v62
	v_add_f32_e32 v62, v88, v62
	v_add_f32_e32 v62, v89, v62
	v_add_f32_e32 v62, v94, v62
	v_add_f32_e32 v62, v95, v62
	v_add_f32_e32 v62, v100, v62
	v_add_f32_e32 v62, v101, v62
	s_nop 1
	v_mov_b32_dpp v63, v62 quad_perm:[1,0,3,2] row_mask:0xf bank_mask:0xf
	v_lshl_add_u64 v[102:103], v[154:155], 0, v[68:69]
	ds_read_b128 v[68:71], v184
	ds_read_b128 v[72:75], v184 offset:16
	ds_read_b128 v[76:79], v184 offset:32
	ds_read_b128 v[80:83], v184 offset:48
	ds_read_b128 v[58:61], v184 offset:64
	s_waitcnt lgkmcnt(5)
	v_add_f32_e32 v62, v62, v63
	s_nop 1
	v_mov_b32_dpp v63, v62 quad_perm:[2,3,0,1] row_mask:0xf bank_mask:0xf
	s_waitcnt lgkmcnt(0)
; DI unsigned pk2(float lo, float hi) { f32x2 v = {lo, hi}; bf16x2_t b = __builtin_convertvector(v, bf16x2_t); return __builtin_bit_cast(unsigned, b); }
; DI float lo_bf(unsigned u) { return __uint_as_float(u << 16); }
; DI float hi_bf(unsigned u) { return __uint_as_float(u & 0xffff0000u); }
; DI void scan_helper_step(const ScanH& k, int n, u32x4 (&stL)[14], const u32x4 (&stS)[14]) {
;     ...
;     const float rs = __builtin_amdgcn_rsqf(ss * (1.f / 128.f) + RMS_EPS);
;     bf16_t* mp = k.MIX + (size_t)(tokb + k.pt) * DM + k.h * 128 + 32 * k.pseg;
; #pragma unroll
;     for (int i = 0; i < 4; ++i) { u32x4 res;
; #pragma unroll
;         for (int j = 0; j < 4; ++j) { const int e = 8 * i + 2 * j;
;             const float a0 = lo_bf(ov4[i][j]) * rs * gmL[e] * lo_bf(zz[i][j]), a1 = hi_bf(ov4[i][j]) * rs * gmL[e + 1] * hi_bf(zz[i][j]); res[j] = pk2(a0, a1); }
;         *(u32x4*)(mp + 8 * i) = res; }
	v_add_f32_e32 v62, v62, v63
	v_fmamk_f32 v62, v62, 0x3c000000, v231
	v_rsq_f32_e32 v66, v62
	s_nop 0
	v_pk_mul_f32 v[62:63], v[66:67], v[198:199] op_sel_hi:[0,1]
	v_pk_mul_f32 v[64:65], v[66:67], v[188:189] op_sel_hi:[0,1]
	v_pk_mul_f32 v[62:63], v[68:69], v[62:63]
	v_pk_mul_f32 v[64:65], v[70:71], v[64:65]
	v_pk_mul_f32 v[62:63], v[62:63], v[202:203]
	v_pk_mul_f32 v[64:65], v[64:65], v[192:193]
	v_cvt_pk_bf16_f32 v62, v62, v63
	v_cvt_pk_bf16_f32 v63, v64, v65
	v_pk_mul_f32 v[64:65], v[66:67], v[108:109] op_sel_hi:[0,1]
	v_pk_mul_f32 v[68:69], v[66:67], v[104:105] op_sel_hi:[0,1]
	v_pk_mul_f32 v[64:65], v[72:73], v[64:65]
	v_pk_mul_f32 v[68:69], v[74:75], v[68:69]
	v_pk_mul_f32 v[64:65], v[64:65], v[112:113]
	v_pk_mul_f32 v[68:69], v[68:69], v[248:249]
	v_cvt_pk_bf16_f32 v64, v64, v65
	v_cvt_pk_bf16_f32 v65, v68, v69
	global_store_dwordx4 v[102:103], v[62:65], off
	v_pk_mul_f32 v[68:69], v[66:67], v[250:251] op_sel_hi:[0,1]
	v_pk_mul_f32 v[68:69], v[82:83], v[68:69]
	v_pk_mul_f32 v[62:63], v[66:67], v[218:219] op_sel_hi:[0,1]
	v_pk_mul_f32 v[64:65], v[66:67], v[212:213] op_sel_hi:[0,1]
	v_pk_mul_f32 v[62:63], v[76:77], v[62:63]
	v_pk_mul_f32 v[64:65], v[78:79], v[64:65]
	v_pk_mul_f32 v[62:63], v[62:63], v[220:221]
	v_pk_mul_f32 v[64:65], v[64:65], v[216:217]
	v_cvt_pk_bf16_f32 v62, v62, v63
	v_cvt_pk_bf16_f32 v63, v64, v65
	v_pk_mul_f32 v[64:65], v[66:67], v[208:209] op_sel_hi:[0,1]
	v_pk_mul_f32 v[64:65], v[80:81], v[64:65]
	v_pk_mul_f32 v[68:69], v[68:69], v[244:245]
	v_pk_mul_f32 v[64:65], v[64:65], v[210:211]
	s_nop 0
	v_cvt_pk_bf16_f32 v64, v64, v65
	v_cvt_pk_bf16_f32 v65, v68, v69
	global_store_dwordx4 v[102:103], v[62:65], off offset:16
	s_nop 1
	v_pk_mul_f32 v[62:63], v[66:67], v[224:225] op_sel_hi:[0,1]
	v_pk_mul_f32 v[58:59], v[58:59], v[62:63]
	v_pk_mul_f32 v[62:63], v[66:67], v[246:247] op_sel_hi:[0,1]
	v_pk_mul_f32 v[60:61], v[62:63], v[60:61]
	v_lshlrev_b32_e32 v62, 16, v241
	v_and_b32_e32 v63, 0xffff0000, v241
	v_pk_mul_f32 v[58:59], v[58:59], v[228:229]
	v_pk_mul_f32 v[60:61], v[60:61], v[62:63]
	v_cvt_pk_bf16_f32 v58, v58, v59
	v_cvt_pk_bf16_f32 v59, v60, v61
	v_mov_b32_e32 v60, v84
	v_mov_b32_e32 v61, v86
	v_pk_mul_f32 v[64:65], v[66:67], v[60:61] op_sel_hi:[0,1]
	ds_read_b128 v[60:63], v184 offset:80
	v_mov_b32_e32 v86, v85
	s_waitcnt lgkmcnt(0)
	v_pk_mul_f32 v[60:61], v[64:65], v[60:61]
	v_lshlrev_b32_e32 v64, 16, v242
	v_and_b32_e32 v65, 0xffff0000, v242
	v_pk_mul_f32 v[60:61], v[60:61], v[64:65]
	v_pk_mul_f32 v[64:65], v[66:67], v[86:87] op_sel_hi:[0,1]
	v_pk_mul_f32 v[62:63], v[64:65], v[62:63]
	v_lshlrev_b32_e32 v64, 16, v243
	v_and_b32_e32 v65, 0xffff0000, v243
	v_pk_mul_f32 v[62:63], v[62:63], v[64:65]
	v_cvt_pk_bf16_f32 v60, v60, v61
	v_cvt_pk_bf16_f32 v61, v62, v63
	global_store_dwordx4 v[102:103], v[58:61], off offset:32
	s_nop 1
	v_mov_b32_e32 v58, v90
	v_mov_b32_e32 v59, v92
	v_pk_mul_f32 v[62:63], v[66:67], v[58:59] op_sel_hi:[0,1]
	ds_read_b128 v[58:61], v184 offset:96
	v_mov_b32_e32 v92, v91
	s_waitcnt lgkmcnt(0)
	v_pk_mul_f32 v[58:59], v[62:63], v[58:59]
	v_lshlrev_b32_e32 v62, 16, v236
	v_and_b32_e32 v63, 0xffff0000, v236
	v_pk_mul_f32 v[58:59], v[58:59], v[62:63]
	v_pk_mul_f32 v[62:63], v[66:67], v[92:93] op_sel_hi:[0,1]
	v_pk_mul_f32 v[60:61], v[62:63], v[60:61]
	v_lshlrev_b32_e32 v62, 16, v237
	v_and_b32_e32 v63, 0xffff0000, v237
	v_pk_mul_f32 v[60:61], v[60:61], v[62:63]
	v_cvt_pk_bf16_f32 v58, v58, v59
	v_cvt_pk_bf16_f32 v59, v60, v61
	v_mov_b32_e32 v60, v96
	v_mov_b32_e32 v61, v98
	v_pk_mul_f32 v[64:65], v[66:67], v[60:61] op_sel_hi:[0,1]
	ds_read_b128 v[60:63], v184 offset:112
	v_mov_b32_e32 v98, v97
	s_waitcnt lgkmcnt(0)
	v_pk_mul_f32 v[60:61], v[64:65], v[60:61]
	v_lshlrev_b32_e32 v64, 16, v238
	v_and_b32_e32 v65, 0xffff0000, v238
	v_pk_mul_f32 v[60:61], v[60:61], v[64:65]
	v_pk_mul_f32 v[64:65], v[66:67], v[98:99] op_sel_hi:[0,1]
	v_pk_mul_f32 v[62:63], v[64:65], v[62:63]
	v_lshlrev_b32_e32 v64, 16, v239
	v_and_b32_e32 v65, 0xffff0000, v239
	v_pk_mul_f32 v[62:63], v[62:63], v[64:65]
	v_cvt_pk_bf16_f32 v60, v60, v61
	v_cvt_pk_bf16_f32 v61, v62, v63
	global_store_dwordx4 v[102:103], v[58:61], off offset:48
	s_cbranch_scc0 .LBB0_198
	s_waitcnt vmcnt(0)
	v_mov_b64_e32 v[250:251], 0xaff
